# GDN scan MFMA waves: next-chunk staging block (address math, LDS-DMA pieces, u/decay loads) interleaved with the v_new MFMA block instead of preceding it
# speedup vs baseline: 1.0167x; 1.0037x over previous
.LBB0_445:
	s_and_b64 vcc, exec, s[24:25]
	s_cbranch_vccnz .Lcw_compute
	s_add_i32 s58, s29, 1
	s_cmpk_lg_i32 s56, 0xfc0
	s_cselect_b32 s31, s58, 63
	s_add_u32 s38, s34, s31
	v_mov_b32_e32 v106, v180
	s_addc_u32 s39, s35, 0
	s_bitcmp1_b32 s57, 0
	v_ashrrev_i32_e32 v107, 4, v106
	v_add_u32_e32 v2, s52, v107
	s_cselect_b32 s0, 0xe000, 0
	v_xor_b32_e32 v4, v2, v106
	s_add_i32 s37, s27, s0
	v_ashrrev_i32_e32 v108, 3, v106
	s_lshl_b64 s[0:1], s[38:39], 13
	s_lshl_b64 s[60:61], s[38:39], 14
	v_lshlrev_b32_e32 v2, 7, v2
	v_lshlrev_b32_e32 v4, 3, v4
	s_add_u32 s62, s43, s60
	v_and_or_b32 v2, v4, s50, v2
	v_add_u32_e32 v4, s53, v108
	s_addc_u32 s63, s44, s61
	v_lshrrev_b32_e32 v5, 1, v4
	s_add_u32 s64, s15, s60
	v_xor_b32_e32 v5, v5, v106
	s_addc_u32 s65, s19, s61
	s_add_i32 s59, s37, 0x4000
	v_lshlrev_b32_e32 v4, 6, v4
	v_lshlrev_b32_e32 v5, 3, v5
	v_lshlrev_b64 v[102:103], 1, v[2:3]
	s_add_u32 s60, s45, s60
	v_and_or_b32 v4, v5, 56, v4
	v_lshl_add_u64 v[104:105], s[62:63], 0, v[102:103]
	s_mov_b32 m0, s37
	v_mov_b32_e32 v5, v3
	s_addc_u32 s61, s46, s61
	s_add_i32 s66, s37, 0x8000
	global_load_lds_dwordx4 v[104:105], off
	v_lshl_add_u64 v[102:103], s[64:65], 0, v[102:103]
	s_mov_b32 m0, s59
	v_lshlrev_b64 v[4:5], 1, v[4:5]
	global_load_lds_dwordx4 v[102:103], off
	v_lshl_add_u64 v[102:103], s[60:61], 0, v[4:5]
	s_mov_b32 m0, s66
	v_add_u32_e32 v2, s54, v107
	global_load_lds_dwordx4 v[102:103], off
	v_xor_b32_e32 v102, v2, v106
	v_lshlrev_b32_e32 v2, 7, v2
	v_lshlrev_b32_e32 v102, 3, v102
	v_and_or_b32 v2, v102, s50, v2
	v_add_u32_e32 v102, s55, v108
	v_lshrrev_b32_e32 v103, 1, v102
	v_lshlrev_b64 v[104:105], 1, v[2:3]
	v_xor_b32_e32 v103, v103, v106
	v_lshl_add_u64 v[106:107], s[62:63], 0, v[104:105]
	s_add_i32 m0, s37, 0x2000
	v_lshlrev_b32_e32 v102, 6, v102
	v_lshlrev_b32_e32 v103, 3, v103
	global_load_lds_dwordx4 v[106:107], off
	v_lshl_add_u64 v[104:105], s[64:65], 0, v[104:105]
	s_add_i32 m0, s37, 0x6000
	v_and_or_b32 v102, v103, 56, v102
	global_load_lds_dwordx4 v[104:105], off
	v_mov_b32_e32 v103, v3
	s_add_i32 m0, s37, 0xa000
	v_lshl_add_u64 v[102:103], v[102:103], 1, s[60:61]
	s_add_u32 s0, s33, s0
	global_load_lds_dwordx4 v[102:103], off
	s_addc_u32 s1, s40, s1
	s_add_i32 m0, s37, 0xc000
	v_lshl_add_u64 v[4:5], s[0:1], 0, v[4:5]
	s_and_b64 s[0:1], s[24:25], exec
	s_cselect_b32 s0, s31, s29
	s_mul_hi_u32 s1, s26, s0
	s_mul_i32 s0, s26, s0
	global_load_lds_dwordx4 v[4:5], off
	v_lshl_add_u64 v[4:5], s[0:1], 1, v[162:163]
	s_mov_b32 s29, s9
	v_lshl_add_u64 v[102:103], v[4:5], 0, s[8:9]
	v_lshl_add_u64 v[104:105], v[4:5], 0, s[28:29]
	s_mov_b32 s37, s9
	s_mov_b32 s31, s9
	v_lshl_add_u64 v[106:107], v[104:105], 0, s[8:9]
	global_load_dwordx2 v[170:171], v[4:5], off
	global_load_dwordx2 v[168:169], v[102:103], off
	global_load_dwordx2 v[164:165], v[104:105], off
	global_load_dwordx2 v[160:161], v[106:107], off
	v_lshl_add_u64 v[102:103], v[4:5], 0, s[36:37]
	v_lshl_add_u64 v[4:5], v[4:5], 0, s[30:31]
	v_lshl_add_u64 v[104:105], v[102:103], 0, s[8:9]
	v_lshl_add_u64 v[106:107], v[4:5], 0, s[8:9]
	global_load_dwordx2 v[158:159], v[102:103], off
	global_load_dwordx2 v[156:157], v[104:105], off
	global_load_dwordx2 v[154:155], v[4:5], off
	global_load_dwordx2 v[152:153], v[106:107], off
	s_and_b64 vcc, exec, s[6:7]
	s_cbranch_vccnz .Lfin_stores
	s_lshl_b64 s[0:1], s[38:39], 2
	s_add_u32 s0, s41, s0
	s_addc_u32 s1, s42, s1
	global_load_dword v147, v3, s[0:1]
	s_branch .LBB0_447

.Lcw_compute:
	s_add_i32 s0, s57, -1
	s_and_b32 s0, s0, 1
	s_mul_i32 s1, s0, 0xe000
	s_add_i32 s1, s1, 0
	v_add_u32_e32 v2, s1, v172
	v_add_u32_e32 v4, v2, v173
	ds_read_b128 v[102:105], v4
	v_cvt_pk_bf16_f32 v110, v22, v23
	v_cvt_pk_bf16_f32 v111, v24, v25
	v_cvt_pk_bf16_f32 v112, v6, v7
	v_cvt_pk_bf16_f32 v113, v8, v9
	v_cvt_pk_bf16_f32 v114, v10, v11
	v_cvt_pk_bf16_f32 v115, v12, v13
	v_cvt_pk_bf16_f32 v116, v18, v19
	v_cvt_pk_bf16_f32 v117, v20, v21
	v_add_u32_e32 v5, v2, v176
	ds_read_b128 v[106:109], v5
	ds_read_b128 v[130:133], v4 offset:4096
	s_waitcnt lgkmcnt(0)
	v_mfma_f32_16x16x32_bf16 v[134:137], v[102:105], v[110:113], v[94:97]
	v_mov_b32_e32 v221, 0
	s_add_i32 s58, s29, 1
	s_cmpk_lg_i32 s56, 0xfc0
	s_cselect_b32 s31, s58, 63
	v_cvt_pk_bf16_f32 v118, v30, v31
	v_cvt_pk_bf16_f32 v119, v32, v33
	v_cvt_pk_bf16_f32 v120, v26, v27
	v_mfma_f32_16x16x32_bf16 v[98:101], v[102:105], v[114:117], v[98:101]
	s_add_u32 s38, s34, s31
	v_mov_b32_e32 v228, v180
	s_addc_u32 s39, s35, 0
	s_bitcmp1_b32 s57, 0
	v_cvt_pk_bf16_f32 v121, v28, v29
	v_cvt_pk_bf16_f32 v122, v14, v15
	v_cvt_pk_bf16_f32 v123, v16, v17
	v_cvt_pk_bf16_f32 v124, v34, v35
	v_cvt_pk_bf16_f32 v125, v36, v37
	v_add_u32_e32 v244, v2, v178
	ds_read_b128 v[102:105], v244
	ds_read_b128 v[204:207], v5 offset:4096
	v_mfma_f32_16x16x32_bf16 v[134:137], v[106:109], v[118:121], v[134:137]
	v_ashrrev_i32_e32 v229, 4, v228
	v_add_u32_e32 v220, s52, v229
	s_cselect_b32 s72, 0xe000, 0
	v_xor_b32_e32 v222, v220, v228
	v_cvt_pk_bf16_f32 v126, v38, v39
	v_cvt_pk_bf16_f32 v127, v40, v41
	v_cvt_pk_bf16_f32 v128, v62, v63
	v_mfma_f32_16x16x32_bf16 v[106:109], v[106:109], v[122:125], v[98:101]
	s_add_i32 s37, s27, s72
	v_ashrrev_i32_e32 v230, 3, v228
	s_lshl_b64 s[72:73], s[38:39], 13
	s_lshl_b64 s[60:61], s[38:39], 14
	v_cvt_pk_bf16_f32 v129, v64, v65
	v_cvt_pk_bf16_f32 v94, v42, v43
	v_cvt_pk_bf16_f32 v95, v44, v45
	v_mfma_f32_16x16x32_bf16 v[86:89], v[130:133], v[110:113], v[86:89]
	v_lshlrev_b32_e32 v220, 7, v220
	v_lshlrev_b32_e32 v222, 3, v222
	s_add_u32 s62, s43, s60
	v_and_or_b32 v220, v222, s50, v220
	v_cvt_pk_bf16_f32 v96, v50, v51
	v_cvt_pk_bf16_f32 v97, v52, v53
	v_add_u32_e32 v245, v2, v179
	v_mfma_f32_16x16x32_bf16 v[90:93], v[130:133], v[114:117], v[90:93]
	v_add_u32_e32 v222, s53, v230
	s_addc_u32 s63, s44, s61
	v_lshrrev_b32_e32 v223, 1, v222
	s_add_u32 s64, s15, s60
	ds_read_b128 v[208:211], v245
	ds_read_b128 v[212:215], v244 offset:4096
	v_cvt_pk_bf16_f32 v98, v58, v59
	v_cvt_pk_bf16_f32 v99, v60, v61
	s_waitcnt lgkmcnt(0)
	v_mfma_f32_16x16x32_bf16 v[134:137], v[102:105], v[126:129], v[134:137]
	v_xor_b32_e32 v223, v223, v228
	s_addc_u32 s65, s19, s61
	s_add_i32 s59, s37, 0x4000
	v_lshlrev_b32_e32 v222, 6, v222
	v_cvt_pk_bf16_f32 v100, v46, v47
	v_cvt_pk_bf16_f32 v101, v48, v49
	v_cvt_pk_bf16_f32 v216, v54, v55
	v_mfma_f32_16x16x32_bf16 v[102:105], v[102:105], v[94:97], v[106:109]
	v_lshlrev_b32_e32 v223, 3, v223
	v_lshlrev_b64 v[224:225], 1, v[220:221]
	s_add_u32 s60, s45, s60
	v_and_or_b32 v222, v223, 56, v222
	v_cvt_pk_bf16_f32 v217, v56, v57
	v_cvt_pk_bf16_f32 v218, v66, v67
	v_cvt_pk_bf16_f32 v219, v68, v69
	ds_read_b128 v[106:109], v245 offset:4096
	v_mfma_f32_16x16x32_bf16 v[86:89], v[204:207], v[118:121], v[86:89]
	v_lshl_add_u64 v[226:227], s[62:63], 0, v[224:225]
	s_mov_b32 m0, s37
	v_mov_b32_e32 v223, v3
	s_addc_u32 s61, s46, s61
	v_mfma_f32_16x16x32_bf16 v[90:93], v[204:207], v[122:125], v[90:93]
	s_add_i32 s66, s37, 0x8000
	global_load_lds_dwordx4 v[226:227], off
	v_lshl_add_u64 v[224:225], s[64:65], 0, v[224:225]
	s_mov_b32 m0, s59
	v_mfma_f32_16x16x32_bf16 v[86:89], v[212:215], v[126:129], v[86:89]
	v_lshlrev_b64 v[222:223], 1, v[222:223]
	global_load_lds_dwordx4 v[224:225], off
	v_lshl_add_u64 v[224:225], s[60:61], 0, v[222:223]
	s_mov_b32 m0, s66
	v_mfma_f32_16x16x32_bf16 v[90:93], v[212:215], v[94:97], v[90:93]
	v_add_u32_e32 v220, s54, v229
	global_load_lds_dwordx4 v[224:225], off
	v_xor_b32_e32 v224, v220, v228
	v_lshlrev_b32_e32 v220, 7, v220
	s_waitcnt lgkmcnt(0)
	v_mfma_f32_16x16x32_bf16 v[86:89], v[106:109], v[98:101], v[86:89]
	v_lshlrev_b32_e32 v224, 3, v224
	v_and_or_b32 v220, v224, s50, v220
	v_add_u32_e32 v224, s55, v230
	v_lshrrev_b32_e32 v225, 1, v224
	v_mfma_f32_16x16x32_bf16 v[90:93], v[106:109], v[216:219], v[90:93]
	v_lshlrev_b64 v[226:227], 1, v[220:221]
	v_xor_b32_e32 v225, v225, v228
	v_lshl_add_u64 v[228:229], s[62:63], 0, v[226:227]
	s_add_i32 m0, s37, 0x2000
	ds_read_b128 v[106:109], v4 offset:8192
	ds_read_b128 v[130:133], v4 offset:12288
	s_waitcnt lgkmcnt(0)
	v_mfma_f32_16x16x32_bf16 v[78:81], v[106:109], v[110:113], v[78:81]
	v_lshlrev_b32_e32 v224, 6, v224
	v_lshlrev_b32_e32 v225, 3, v225
	global_load_lds_dwordx4 v[228:229], off
	v_lshl_add_u64 v[226:227], s[64:65], 0, v[226:227]
	v_mfma_f32_16x16x32_bf16 v[82:85], v[106:109], v[114:117], v[82:85]
	s_add_i32 m0, s37, 0x6000
	v_and_or_b32 v224, v225, 56, v224
	global_load_lds_dwordx4 v[226:227], off
	v_mov_b32_e32 v225, v3
	ds_read_b128 v[106:109], v5 offset:8192
	ds_read_b128 v[204:207], v5 offset:12288
	v_mfma_f32_16x16x32_bf16 v[70:73], v[130:133], v[110:113], v[70:73]
	s_add_i32 m0, s37, 0xa000
	v_lshl_add_u64 v[224:225], v[224:225], 1, s[60:61]
	s_add_u32 s72, s33, s72
	global_load_lds_dwordx4 v[224:225], off
	v_mfma_f32_16x16x32_bf16 v[134:137], v[208:211], v[98:101], v[134:137]
	s_addc_u32 s73, s40, s73
	s_add_i32 m0, s37, 0xc000
	v_lshl_add_u64 v[222:223], s[72:73], 0, v[222:223]
	s_and_b64 s[72:73], s[24:25], exec
	v_mfma_f32_16x16x32_bf16 v[102:105], v[208:211], v[216:219], v[102:105]
	s_cselect_b32 s72, s31, s29
	s_mul_hi_u32 s73, s26, s72
	s_mul_i32 s72, s26, s72
	global_load_lds_dwordx4 v[222:223], off
	s_waitcnt lgkmcnt(0)
	v_mfma_f32_16x16x32_bf16 v[78:81], v[106:109], v[118:121], v[78:81]
	v_lshl_add_u64 v[222:223], s[72:73], 1, v[162:163]
	s_mov_b32 s29, s9
	v_lshl_add_u64 v[224:225], v[222:223], 0, s[8:9]
	v_lshl_add_u64 v[226:227], v[222:223], 0, s[28:29]
	v_mfma_f32_16x16x32_bf16 v[82:85], v[106:109], v[122:125], v[82:85]
	s_mov_b32 s37, s9
	s_mov_b32 s31, s9
	v_lshl_add_u64 v[228:229], v[226:227], 0, s[8:9]
	global_load_dwordx2 v[170:171], v[222:223], off
	ds_read_b128 v[106:109], v244 offset:8192
	ds_read_b128 v[208:211], v244 offset:12288
	v_mfma_f32_16x16x32_bf16 v[74:77], v[130:133], v[114:117], v[74:77]
	global_load_dwordx2 v[168:169], v[224:225], off
	global_load_dwordx2 v[164:165], v[226:227], off
	global_load_dwordx2 v[160:161], v[228:229], off
	v_lshl_add_u64 v[224:225], v[222:223], 0, s[36:37]
	v_mfma_f32_16x16x32_bf16 v[70:73], v[204:207], v[118:121], v[70:73]
	v_lshl_add_u64 v[222:223], v[222:223], 0, s[30:31]
	v_lshl_add_u64 v[226:227], v[224:225], 0, s[8:9]
	v_lshl_add_u64 v[228:229], v[222:223], 0, s[8:9]
	global_load_dwordx2 v[158:159], v[224:225], off
	s_waitcnt lgkmcnt(0)
	v_mfma_f32_16x16x32_bf16 v[78:81], v[106:109], v[126:129], v[78:81]
	global_load_dwordx2 v[156:157], v[226:227], off
	global_load_dwordx2 v[154:155], v[222:223], off
	global_load_dwordx2 v[152:153], v[228:229], off
	s_lshl_b64 s[72:73], s[38:39], 2
	v_mfma_f32_16x16x32_bf16 v[82:85], v[106:109], v[94:97], v[82:85]
	s_add_u32 s72, s41, s72
	s_addc_u32 s73, s42, s73
	global_load_dword v147, v3, s[72:73]
	ds_read_b128 v[106:109], v245 offset:8192
	ds_read_b128 v[212:215], v245 offset:12288
	v_mfma_f32_16x16x32_bf16 v[74:77], v[204:207], v[122:125], v[74:77]
	v_mfma_f32_16x16x32_bf16 v[70:73], v[208:211], v[126:129], v[70:73]
	s_waitcnt lgkmcnt(0)
	v_mfma_f32_16x16x32_bf16 v[78:81], v[106:109], v[98:101], v[78:81]
	v_mfma_f32_16x16x32_bf16 v[82:85], v[106:109], v[216:219], v[82:85]
	v_mfma_f32_16x16x32_bf16 v[74:77], v[208:211], v[94:97], v[74:77]
	v_mfma_f32_16x16x32_bf16 v[130:133], v[212:215], v[98:101], v[70:73]
	v_mfma_f32_16x16x32_bf16 v[206:209], v[212:215], v[216:219], v[74:77]
	s_nop 1
	ds_read_b128 v[70:73], v4 offset:16384
	ds_read_b128 v[210:213], v4 offset:20480
	ds_read_b128 v[220:223], v5 offset:16384
	ds_read_b128 v[224:227], v5 offset:20480
	ds_read_b128 v[228:231], v244 offset:16384
	s_waitcnt lgkmcnt(0)
	v_mfma_f32_16x16x32_bf16 v[74:77], v[70:73], v[110:113], 0
	v_mfma_f32_16x16x32_bf16 v[106:109], v[70:73], v[114:117], 0
	v_cvt_pk_bf16_f32 v70, v134, v135
	v_cvt_pk_bf16_f32 v71, v136, v137
	v_cvt_pk_bf16_f32 v72, v86, v87
	v_mfma_f32_16x16x32_bf16 v[74:77], v[220:223], v[118:121], v[74:77]
	v_cvt_pk_bf16_f32 v73, v88, v89
	v_mfma_f32_16x16x32_bf16 v[134:137], v[220:223], v[122:125], v[106:109]
	ds_read_b128 v[220:223], v245 offset:16384
	ds_read_b128 v[232:235], v244 offset:20480
	s_nop 0
	v_add_u32_e32 v109, s1, v167
	v_mfma_f32_16x16x32_bf16 v[74:77], v[228:231], v[126:129], v[74:77]
	v_add_u32_e32 v2, v109, v174
	v_cvt_pk_bf16_f32 v106, v78, v79
	v_add_u32_e32 v204, v109, v175
	v_mfma_f32_16x16x32_bf16 v[86:89], v[228:231], v[94:97], v[134:137]
	s_nop 2
	ds_read_b128 v[134:137], v2 offset:49152
	ds_read_b128 v[228:231], v245 offset:20480
	v_cvt_pk_bf16_f32 v107, v80, v81
	v_cvt_pk_bf16_f32 v108, v130, v131
	s_waitcnt lgkmcnt(0)
	v_mfma_f32_16x16x32_bf16 v[76:79], v[220:223], v[98:101], v[74:77]
	v_cvt_pk_bf16_f32 v109, v132, v133
	v_mfma_f32_16x16x32_bf16 v[86:89], v[220:223], v[216:219], v[86:89]
	ds_read_b128 v[220:223], v204 offset:49152
	ds_read_b128 v[236:239], v2 offset:51200
	v_cvt_pk_bf16_f32 v74, v102, v103
	v_cvt_pk_bf16_f32 v102, v82, v83
	v_mfma_f32_16x16x32_bf16 v[78:81], v[134:137], v[70:73], v[76:79]
	v_cvt_pk_bf16_f32 v103, v84, v85
	v_cvt_pk_bf16_f32 v75, v104, v105
	v_cvt_pk_bf16_f32 v104, v206, v207
	s_waitcnt lgkmcnt(0)
	v_mfma_f32_16x16x32_bf16 v[240:243], v[220:223], v[106:109], v[78:81]
	v_cvt_pk_bf16_f32 v76, v90, v91
	v_cvt_pk_bf16_f32 v77, v92, v93
	ds_read_b128 v[90:93], v204 offset:51200
	v_mfma_f32_16x16x32_bf16 v[78:81], v[210:213], v[110:113], 0
	v_cvt_pk_bf16_f32 v105, v208, v209
	v_mfma_f32_16x16x32_bf16 v[82:85], v[210:213], v[114:117], 0
	v_mfma_f32_16x16x32_bf16 v[78:81], v[224:227], v[118:121], v[78:81]
	v_mfma_f32_16x16x32_bf16 v[82:85], v[224:227], v[122:125], v[82:85]
	v_mfma_f32_16x16x32_bf16 v[78:81], v[232:235], v[126:129], v[78:81]
	v_mfma_f32_16x16x32_bf16 v[82:85], v[232:235], v[94:97], v[82:85]
	v_mfma_f32_16x16x32_bf16 v[78:81], v[228:231], v[98:101], v[78:81]
	v_mfma_f32_16x16x32_bf16 v[82:85], v[228:231], v[216:219], v[82:85]
	v_mfma_f32_16x16x32_bf16 v[78:81], v[236:239], v[70:73], v[78:81]
	v_mfma_f32_16x16x32_bf16 v[82:85], v[236:239], v[74:77], v[82:85]
	v_mfma_f32_16x16x32_bf16 v[86:89], v[134:137], v[74:77], v[86:89]
	s_waitcnt lgkmcnt(0)
	v_mfma_f32_16x16x32_bf16 v[134:137], v[90:93], v[106:109], v[78:81]
	v_mfma_f32_16x16x32_bf16 v[130:133], v[90:93], v[102:105], v[82:85]
	s_nop 2
	ds_read_b128 v[78:81], v4 offset:24576
	ds_read_b128 v[82:85], v4 offset:28672
	ds_read_b128 v[90:93], v5 offset:24576
	ds_read_b128 v[210:213], v5 offset:28672
	v_mfma_f32_16x16x32_bf16 v[206:209], v[220:223], v[102:105], v[86:89]
	s_waitcnt lgkmcnt(0)
	v_mfma_f32_16x16x32_bf16 v[86:89], v[78:81], v[110:113], 0
	v_mfma_f32_16x16x32_bf16 v[78:81], v[78:81], v[114:117], 0
	v_mfma_f32_16x16x32_bf16 v[86:89], v[90:93], v[118:121], v[86:89]
	v_mfma_f32_16x16x32_bf16 v[78:81], v[90:93], v[122:125], v[78:81]
	ds_read_b128 v[90:93], v244 offset:24576
	ds_read_b128 v[220:223], v244 offset:28672
	s_waitcnt lgkmcnt(0)
	v_mfma_f32_16x16x32_bf16 v[86:89], v[90:93], v[126:129], v[86:89]
	v_mfma_f32_16x16x32_bf16 v[78:81], v[90:93], v[94:97], v[78:81]
	ds_read_b128 v[90:93], v245 offset:24576
	ds_read_b128 v[224:227], v245 offset:28672
	s_waitcnt lgkmcnt(0)
	v_mfma_f32_16x16x32_bf16 v[86:89], v[90:93], v[98:101], v[86:89]
	v_mfma_f32_16x16x32_bf16 v[78:81], v[90:93], v[216:219], v[78:81]
	ds_read_b128 v[90:93], v2 offset:53248
	ds_read_b128 v[228:231], v2 offset:55296
	ds_read_b128 v[232:235], v204 offset:53248
	ds_read_b128 v[236:239], v204 offset:55296
	s_waitcnt lgkmcnt(0)
	v_mfma_f32_16x16x32_bf16 v[86:89], v[90:93], v[70:73], v[86:89]
	v_mfma_f32_16x16x32_bf16 v[78:81], v[90:93], v[74:77], v[78:81]
	v_mfma_f32_16x16x32_bf16 v[90:93], v[232:235], v[106:109], v[86:89]
	v_mfma_f32_16x16x32_bf16 v[86:89], v[232:235], v[102:105], v[78:81]
	v_mfma_f32_16x16x32_bf16 v[78:81], v[82:85], v[110:113], 0
	v_mfma_f32_16x16x32_bf16 v[82:85], v[82:85], v[114:117], 0
	v_mfma_f32_16x16x32_bf16 v[78:81], v[210:213], v[118:121], v[78:81]
	v_mfma_f32_16x16x32_bf16 v[82:85], v[210:213], v[122:125], v[82:85]
	v_mfma_f32_16x16x32_bf16 v[78:81], v[220:223], v[126:129], v[78:81]
	v_mfma_f32_16x16x32_bf16 v[82:85], v[220:223], v[94:97], v[82:85]
	v_mfma_f32_16x16x32_bf16 v[78:81], v[224:227], v[98:101], v[78:81]
	v_mfma_f32_16x16x32_bf16 v[82:85], v[224:227], v[216:219], v[82:85]
	v_mfma_f32_16x16x32_bf16 v[78:81], v[228:231], v[70:73], v[78:81]
	v_mfma_f32_16x16x32_bf16 v[94:97], v[228:231], v[74:77], v[82:85]
	v_mfma_f32_16x16x32_bf16 v[82:85], v[236:239], v[106:109], v[78:81]
	v_mfma_f32_16x16x32_bf16 v[78:81], v[236:239], v[102:105], v[94:97]
	v_mul_f32_e64 v4, v208, v208
	v_mul_f32_e64 v5, v209, v209
	s_nop 3
	v_pk_mul_f32 v[94:95], v[206:207], v[206:207]
	v_lshl_add_u32 v98, s0, 14, v193
	v_pk_fma_f32 v[96:97], v[242:243], v[242:243], v[4:5]
	v_pk_fma_f32 v[4:5], v[240:241], v[240:241], v[94:95]
	v_cvt_pk_bf16_f32 v95, v240, s0
	v_lshl_add_u32 v100, v149, 1, v98
	ds_write_b16 v100, v95
	v_cvt_pk_bf16_f32 v95, v206, s0
	v_lshl_add_u32 v101, v201, 1, v98
	v_cvt_pk_bf16_f32 v98, v241, s0
	ds_write_b16 v101, v95
	ds_write_b16 v100, v98 offset:256
	v_cvt_pk_bf16_f32 v98, v207, s0
	v_cvt_pk_bf16_f32 v99, v242, s0
	ds_write_b16 v101, v98 offset:256
	ds_write_b16 v100, v99 offset:512
	v_cvt_pk_bf16_f32 v99, v208, s0
	v_mov_b32_dpp v94, v4 quad_perm:[1,0,3,2] row_mask:0xf bank_mask:0xf bound_ctrl:1
	v_mov_b32_dpp v95, v5 quad_perm:[1,0,3,2] row_mask:0xf bank_mask:0xf bound_ctrl:1
	v_mov_b32_dpp v98, v96 quad_perm:[1,0,3,2] row_mask:0xf bank_mask:0xf bound_ctrl:1
	ds_write_b16 v101, v99 offset:512
	v_mov_b32_dpp v99, v97 quad_perm:[1,0,3,2] row_mask:0xf bank_mask:0xf bound_ctrl:1
	v_pk_add_f32 v[4:5], v[4:5], v[94:95]
	v_pk_add_f32 v[96:97], v[96:97], v[98:99]
	v_cvt_pk_bf16_f32 v110, v243, s0
	v_mov_b32_dpp v94, v4 quad_perm:[2,3,0,1] row_mask:0xf bank_mask:0xf bound_ctrl:1
	v_mov_b32_dpp v95, v5 quad_perm:[2,3,0,1] row_mask:0xf bank_mask:0xf bound_ctrl:1
	v_mov_b32_dpp v98, v96 quad_perm:[2,3,0,1] row_mask:0xf bank_mask:0xf bound_ctrl:1
	v_mov_b32_dpp v99, v97 quad_perm:[2,3,0,1] row_mask:0xf bank_mask:0xf bound_ctrl:1
	v_pk_add_f32 v[4:5], v[4:5], v[94:95]
	v_pk_add_f32 v[96:97], v[96:97], v[98:99]
	s_lshl_b32 s1, s0, 10
	v_mov_b32_dpp v94, v4 row_half_mirror row_mask:0xf bank_mask:0xf bound_ctrl:1
	v_mov_b32_dpp v95, v5 row_half_mirror row_mask:0xf bank_mask:0xf bound_ctrl:1
	v_mov_b32_dpp v98, v96 row_half_mirror row_mask:0xf bank_mask:0xf bound_ctrl:1
	v_mov_b32_dpp v99, v97 row_half_mirror row_mask:0xf bank_mask:0xf bound_ctrl:1
	v_pk_add_f32 v[4:5], v[4:5], v[94:95]
	v_pk_add_f32 v[96:97], v[96:97], v[98:99]
	ds_write_b16 v100, v110 offset:768
	v_cvt_pk_bf16_f32 v110, v209, s0
	v_mov_b32_dpp v94, v4 row_mirror row_mask:0xf bank_mask:0xf bound_ctrl:1
	v_mov_b32_dpp v95, v5 row_mirror row_mask:0xf bank_mask:0xf bound_ctrl:1
	v_mov_b32_dpp v98, v96 row_mirror row_mask:0xf bank_mask:0xf bound_ctrl:1
	v_mov_b32_dpp v99, v97 row_mirror row_mask:0xf bank_mask:0xf bound_ctrl:1
	ds_write_b16 v101, v110 offset:768
	v_add_u32_e32 v110, s1, v202
	s_and_saveexec_b64 s[38:39], s[4:5]
	v_pk_add_f32 v[96:97], v[96:97], v[98:99]
	v_pk_add_f32 v[94:95], v[4:5], v[94:95]
	ds_write_b128 v110, v[94:97]
	s_or_b64 exec, exec, s[38:39]
	v_pk_mul_f32 v[4:5], v[132:133], v[132:133]
	v_pk_mul_f32 v[94:95], v[130:131], v[130:131]
	v_pk_fma_f32 v[96:97], v[136:137], v[136:137], v[4:5]
	v_pk_fma_f32 v[4:5], v[134:135], v[134:135], v[94:95]
	v_cvt_pk_bf16_f32 v95, v134, s0
	ds_write_b16 v100, v95 offset:4096
	v_cvt_pk_bf16_f32 v95, v130, s0
	v_cvt_pk_bf16_f32 v98, v135, s0
	ds_write_b16 v101, v95 offset:4096
	ds_write_b16 v100, v98 offset:4352
	v_cvt_pk_bf16_f32 v98, v131, s0
	v_cvt_pk_bf16_f32 v99, v136, s0
	ds_write_b16 v101, v98 offset:4352
	ds_write_b16 v100, v99 offset:4608
	v_cvt_pk_bf16_f32 v99, v132, s0
	v_mov_b32_dpp v94, v4 quad_perm:[1,0,3,2] row_mask:0xf bank_mask:0xf bound_ctrl:1
	v_mov_b32_dpp v95, v5 quad_perm:[1,0,3,2] row_mask:0xf bank_mask:0xf bound_ctrl:1
	v_mov_b32_dpp v98, v96 quad_perm:[1,0,3,2] row_mask:0xf bank_mask:0xf bound_ctrl:1
	ds_write_b16 v101, v99 offset:4608
	v_mov_b32_dpp v99, v97 quad_perm:[1,0,3,2] row_mask:0xf bank_mask:0xf bound_ctrl:1
	v_pk_add_f32 v[4:5], v[4:5], v[94:95]
	v_pk_add_f32 v[96:97], v[96:97], v[98:99]
	v_cvt_pk_bf16_f32 v111, v137, s0
	v_mov_b32_dpp v94, v4 quad_perm:[2,3,0,1] row_mask:0xf bank_mask:0xf bound_ctrl:1
	v_mov_b32_dpp v95, v5 quad_perm:[2,3,0,1] row_mask:0xf bank_mask:0xf bound_ctrl:1
	v_mov_b32_dpp v98, v96 quad_perm:[2,3,0,1] row_mask:0xf bank_mask:0xf bound_ctrl:1
	v_mov_b32_dpp v99, v97 quad_perm:[2,3,0,1] row_mask:0xf bank_mask:0xf bound_ctrl:1
	v_pk_add_f32 v[4:5], v[4:5], v[94:95]
	v_pk_add_f32 v[96:97], v[96:97], v[98:99]
	ds_write_b16 v100, v111 offset:4864
	v_mov_b32_dpp v94, v4 row_half_mirror row_mask:0xf bank_mask:0xf bound_ctrl:1
	v_mov_b32_dpp v95, v5 row_half_mirror row_mask:0xf bank_mask:0xf bound_ctrl:1
	v_mov_b32_dpp v98, v96 row_half_mirror row_mask:0xf bank_mask:0xf bound_ctrl:1
	v_mov_b32_dpp v99, v97 row_half_mirror row_mask:0xf bank_mask:0xf bound_ctrl:1
	v_pk_add_f32 v[4:5], v[4:5], v[94:95]
	v_pk_add_f32 v[96:97], v[96:97], v[98:99]
	v_cvt_pk_bf16_f32 v111, v133, s0
	v_mov_b32_dpp v94, v4 row_mirror row_mask:0xf bank_mask:0xf bound_ctrl:1
	v_mov_b32_dpp v95, v5 row_mirror row_mask:0xf bank_mask:0xf bound_ctrl:1
	v_mov_b32_dpp v98, v96 row_mirror row_mask:0xf bank_mask:0xf bound_ctrl:1
	v_mov_b32_dpp v99, v97 row_mirror row_mask:0xf bank_mask:0xf bound_ctrl:1
	ds_write_b16 v101, v111 offset:4864
	s_and_saveexec_b64 s[38:39], s[4:5]
	v_pk_add_f32 v[96:97], v[96:97], v[98:99]
	v_pk_add_f32 v[94:95], v[4:5], v[94:95]
	ds_write_b128 v110, v[94:97] offset:64
	s_or_b64 exec, exec, s[38:39]
	v_pk_mul_f32 v[94:95], v[86:87], v[86:87]
	v_cvt_pk_bf16_f32 v86, v86, s0
	v_pk_mul_f32 v[4:5], v[88:89], v[88:89]
	ds_write_b16 v101, v86 offset:8192
	v_cvt_pk_bf16_f32 v86, v91, s0
	v_pk_fma_f32 v[96:97], v[92:93], v[92:93], v[4:5]
	v_pk_fma_f32 v[4:5], v[90:91], v[90:91], v[94:95]
	v_cvt_pk_bf16_f32 v90, v90, s0
	ds_write_b16 v100, v86 offset:8448
	v_cvt_pk_bf16_f32 v86, v87, s0
	v_cvt_pk_bf16_f32 v87, v92, s0
	ds_write_b16 v100, v90 offset:8192
	ds_write_b16 v101, v86 offset:8448
	ds_write_b16 v100, v87 offset:8704
	v_cvt_pk_bf16_f32 v87, v88, s0
	v_mov_b32_dpp v94, v4 quad_perm:[1,0,3,2] row_mask:0xf bank_mask:0xf bound_ctrl:1
	v_mov_b32_dpp v95, v5 quad_perm:[1,0,3,2] row_mask:0xf bank_mask:0xf bound_ctrl:1
	v_mov_b32_dpp v86, v96 quad_perm:[1,0,3,2] row_mask:0xf bank_mask:0xf bound_ctrl:1
	ds_write_b16 v101, v87 offset:8704
	v_mov_b32_dpp v87, v97 quad_perm:[1,0,3,2] row_mask:0xf bank_mask:0xf bound_ctrl:1
	v_pk_add_f32 v[4:5], v[4:5], v[94:95]
	v_pk_add_f32 v[86:87], v[96:97], v[86:87]
	v_cvt_pk_bf16_f32 v88, v93, s0
	v_mov_b32_dpp v94, v4 quad_perm:[2,3,0,1] row_mask:0xf bank_mask:0xf bound_ctrl:1
	v_mov_b32_dpp v95, v5 quad_perm:[2,3,0,1] row_mask:0xf bank_mask:0xf bound_ctrl:1
	v_mov_b32_dpp v90, v86 quad_perm:[2,3,0,1] row_mask:0xf bank_mask:0xf bound_ctrl:1
	v_mov_b32_dpp v91, v87 quad_perm:[2,3,0,1] row_mask:0xf bank_mask:0xf bound_ctrl:1
	v_pk_add_f32 v[4:5], v[4:5], v[94:95]
	v_pk_add_f32 v[86:87], v[86:87], v[90:91]
	ds_write_b16 v100, v88 offset:8960
	v_mov_b32_dpp v94, v4 row_half_mirror row_mask:0xf bank_mask:0xf bound_ctrl:1
	v_mov_b32_dpp v95, v5 row_half_mirror row_mask:0xf bank_mask:0xf bound_ctrl:1
	v_mov_b32_dpp v90, v86 row_half_mirror row_mask:0xf bank_mask:0xf bound_ctrl:1
	v_mov_b32_dpp v91, v87 row_half_mirror row_mask:0xf bank_mask:0xf bound_ctrl:1
	v_pk_add_f32 v[4:5], v[4:5], v[94:95]
	v_pk_add_f32 v[86:87], v[86:87], v[90:91]
	v_cvt_pk_bf16_f32 v88, v89, s0
	v_mov_b32_dpp v94, v4 row_mirror row_mask:0xf bank_mask:0xf bound_ctrl:1
	v_mov_b32_dpp v95, v5 row_mirror row_mask:0xf bank_mask:0xf bound_ctrl:1
	v_mov_b32_dpp v90, v86 row_mirror row_mask:0xf bank_mask:0xf bound_ctrl:1
	v_mov_b32_dpp v91, v87 row_mirror row_mask:0xf bank_mask:0xf bound_ctrl:1
	ds_write_b16 v101, v88 offset:8960
	s_and_saveexec_b64 s[38:39], s[4:5]
	v_pk_add_f32 v[88:89], v[86:87], v[90:91]
	v_pk_add_f32 v[86:87], v[4:5], v[94:95]
	ds_write_b128 v110, v[86:89] offset:128
	s_or_b64 exec, exec, s[38:39]
	v_pk_mul_f32 v[86:87], v[78:79], v[78:79]
	v_cvt_pk_bf16_f32 v78, v78, s0
	v_pk_mul_f32 v[4:5], v[80:81], v[80:81]
	ds_write_b16 v101, v78 offset:12288
	v_cvt_pk_bf16_f32 v78, v83, s0
	v_pk_fma_f32 v[88:89], v[84:85], v[84:85], v[4:5]
	v_pk_fma_f32 v[4:5], v[82:83], v[82:83], v[86:87]
	v_cvt_pk_bf16_f32 v82, v82, s0
	ds_write_b16 v100, v78 offset:12544
	v_cvt_pk_bf16_f32 v78, v79, s0
	v_cvt_pk_bf16_f32 v79, v84, s0
	ds_write_b16 v100, v82 offset:12288
	ds_write_b16 v101, v78 offset:12544
	ds_write_b16 v100, v79 offset:12800
	v_cvt_pk_bf16_f32 v79, v80, s0
	v_mov_b32_dpp v86, v4 quad_perm:[1,0,3,2] row_mask:0xf bank_mask:0xf bound_ctrl:1
	v_mov_b32_dpp v87, v5 quad_perm:[1,0,3,2] row_mask:0xf bank_mask:0xf bound_ctrl:1
	v_mov_b32_dpp v78, v88 quad_perm:[1,0,3,2] row_mask:0xf bank_mask:0xf bound_ctrl:1
	ds_write_b16 v101, v79 offset:12800
	v_mov_b32_dpp v79, v89 quad_perm:[1,0,3,2] row_mask:0xf bank_mask:0xf bound_ctrl:1
	v_pk_add_f32 v[4:5], v[4:5], v[86:87]
	v_pk_add_f32 v[78:79], v[88:89], v[78:79]
	v_cvt_pk_bf16_f32 v80, v85, s0
	v_mov_b32_dpp v86, v4 quad_perm:[2,3,0,1] row_mask:0xf bank_mask:0xf bound_ctrl:1
	v_mov_b32_dpp v87, v5 quad_perm:[2,3,0,1] row_mask:0xf bank_mask:0xf bound_ctrl:1
	v_mov_b32_dpp v82, v78 quad_perm:[2,3,0,1] row_mask:0xf bank_mask:0xf bound_ctrl:1
	v_mov_b32_dpp v83, v79 quad_perm:[2,3,0,1] row_mask:0xf bank_mask:0xf bound_ctrl:1
	v_pk_add_f32 v[4:5], v[4:5], v[86:87]
	v_pk_add_f32 v[78:79], v[78:79], v[82:83]
	ds_write_b16 v100, v80 offset:13056
	v_mov_b32_dpp v86, v4 row_half_mirror row_mask:0xf bank_mask:0xf bound_ctrl:1
	v_mov_b32_dpp v87, v5 row_half_mirror row_mask:0xf bank_mask:0xf bound_ctrl:1
	v_mov_b32_dpp v82, v78 row_half_mirror row_mask:0xf bank_mask:0xf bound_ctrl:1
	v_mov_b32_dpp v83, v79 row_half_mirror row_mask:0xf bank_mask:0xf bound_ctrl:1
	v_pk_add_f32 v[4:5], v[4:5], v[86:87]
	v_pk_add_f32 v[78:79], v[78:79], v[82:83]
	v_cvt_pk_bf16_f32 v80, v81, s0
	v_mov_b32_dpp v86, v4 row_mirror row_mask:0xf bank_mask:0xf bound_ctrl:1
	v_mov_b32_dpp v87, v5 row_mirror row_mask:0xf bank_mask:0xf bound_ctrl:1
	v_mov_b32_dpp v82, v78 row_mirror row_mask:0xf bank_mask:0xf bound_ctrl:1
	v_mov_b32_dpp v83, v79 row_mirror row_mask:0xf bank_mask:0xf bound_ctrl:1
	ds_write_b16 v101, v80 offset:13056
	s_and_saveexec_b64 s[38:39], s[4:5]
	v_pk_add_f32 v[80:81], v[78:79], v[82:83]
	v_pk_add_f32 v[78:79], v[4:5], v[86:87]
	ds_write_b128 v110, v[78:81] offset:192
	s_or_b64 exec, exec, s[38:39]
	ds_read_b128 v[78:81], v2 offset:32768
	ds_read_b128 v[82:85], v2 offset:34816
	v_pk_mul_f32 v[24:25], v[24:25], v[166:167] op_sel_hi:[1,0]
	v_pk_mul_f32 v[22:23], v[22:23], v[166:167] op_sel_hi:[1,0]
	v_pk_mul_f32 v[12:13], v[12:13], v[166:167] op_sel_hi:[1,0]
	v_pk_mul_f32 v[10:11], v[10:11], v[166:167] op_sel_hi:[1,0]
	v_pk_mul_f32 v[8:9], v[8:9], v[166:167] op_sel_hi:[1,0]
	v_pk_mul_f32 v[6:7], v[6:7], v[166:167] op_sel_hi:[1,0]
	v_pk_mul_f32 v[20:21], v[20:21], v[166:167] op_sel_hi:[1,0]
	s_waitcnt lgkmcnt(0)
	v_mfma_f32_16x16x32_bf16 v[22:25], v[78:81], v[70:73], v[22:25]
	v_mul_f32_e64 v18, v18, v166
	v_mul_f32_e64 v19, v19, v166
	v_pk_mul_f32 v[32:33], v[32:33], v[166:167] op_sel_hi:[1,0]
	v_pk_mul_f32 v[30:31], v[30:31], v[166:167] op_sel_hi:[1,0]
	v_mfma_f32_16x16x32_bf16 v[10:13], v[78:81], v[74:77], v[10:13]
	ds_read_b128 v[78:81], v204 offset:32768
	ds_read_b128 v[86:89], v204 offset:34816
	v_pk_mul_f32 v[16:17], v[16:17], v[166:167] op_sel_hi:[1,0]
	v_pk_mul_f32 v[14:15], v[14:15], v[166:167] op_sel_hi:[1,0]
	s_waitcnt lgkmcnt(0)
	v_mfma_f32_16x16x32_bf16 v[22:25], v[78:81], v[106:109], v[22:25]
	v_mul_f32_e64 v28, v28, v166
	v_mul_f32_e64 v29, v29, v166
	v_pk_mul_f32 v[26:27], v[26:27], v[166:167] op_sel_hi:[1,0]
	v_pk_mul_f32 v[36:37], v[36:37], v[166:167] op_sel_hi:[1,0]
	v_mfma_f32_16x16x32_bf16 v[10:13], v[78:81], v[102:105], v[10:13]
	ds_read_b128 v[78:81], v2 offset:36864
	v_pk_mul_f32 v[34:35], v[34:35], v[166:167] op_sel_hi:[1,0]
	v_pk_mul_f32 v[40:41], v[40:41], v[166:167] op_sel_hi:[1,0]
	v_mfma_f32_16x16x32_bf16 v[4:7], v[82:85], v[70:73], v[6:9]
	v_mul_f32_e64 v38, v38, v166
	v_mul_f32_e64 v39, v39, v166
	v_pk_mul_f32 v[44:45], v[44:45], v[166:167] op_sel_hi:[1,0]
	v_pk_mul_f32 v[42:43], v[42:43], v[166:167] op_sel_hi:[1,0]
	v_mfma_f32_16x16x32_bf16 v[18:21], v[82:85], v[74:77], v[18:21]
	ds_read_b128 v[82:85], v2 offset:38912
	v_pk_mul_f32 v[64:65], v[64:65], v[166:167] op_sel_hi:[1,0]
	v_pk_mul_f32 v[62:63], v[62:63], v[166:167] op_sel_hi:[1,0]
	v_mfma_f32_16x16x32_bf16 v[6:9], v[86:89], v[106:109], v[4:7]
	v_mul_f32_e64 v52, v52, v166
	v_mul_f32_e64 v53, v53, v166
	v_pk_mul_f32 v[50:51], v[50:51], v[166:167] op_sel_hi:[1,0]
	v_pk_mul_f32 v[60:61], v[60:61], v[166:167] op_sel_hi:[1,0]
	v_mfma_f32_16x16x32_bf16 v[18:21], v[86:89], v[102:105], v[18:21]
	v_mul_f32_e64 v58, v58, v166
	v_mul_f32_e64 v59, v59, v166
	v_pk_mul_f32 v[56:57], v[56:57], v[166:167] op_sel_hi:[1,0]
	v_pk_mul_f32 v[54:55], v[54:55], v[166:167] op_sel_hi:[1,0]
	s_waitcnt lgkmcnt(0)
	v_mfma_f32_16x16x32_bf16 v[30:33], v[78:81], v[70:73], v[30:33]
	v_mul_f32_e64 v48, v48, v166
	v_mul_f32_e64 v49, v49, v166
	v_pk_mul_f32 v[46:47], v[46:47], v[166:167] op_sel_hi:[1,0]
	v_pk_mul_f32 v[68:69], v[68:69], v[166:167] op_sel_hi:[1,0]
	v_mfma_f32_16x16x32_bf16 v[14:17], v[78:81], v[74:77], v[14:17]
	ds_read_b128 v[78:81], v204 offset:36864
	ds_read_b128 v[86:89], v204 offset:38912
	ds_read_b128 v[90:93], v204 offset:43008
	v_pk_mul_f32 v[66:67], v[66:67], v[166:167] op_sel_hi:[1,0]
	s_waitcnt lgkmcnt(0)
	v_mfma_f32_16x16x32_bf16 v[30:33], v[78:81], v[106:109], v[30:33]
	s_waitcnt vmcnt(0)
	v_lshlrev_b32_e32 v94, 16, v170
	v_and_b32_e32 v95, 0xffff0000, v170
	v_lshlrev_b32_e32 v96, 16, v171
	v_mfma_f32_16x16x32_bf16 v[14:17], v[78:81], v[102:105], v[14:17]
	ds_read_b128 v[78:81], v2 offset:40960
	v_and_b32_e32 v97, 0xffff0000, v171
	v_lshlrev_b32_e32 v98, 16, v168
	v_mfma_f32_16x16x32_bf16 v[26:29], v[82:85], v[70:73], v[26:29]
	v_and_b32_e32 v99, 0xffff0000, v168
	v_lshlrev_b32_e32 v100, 16, v169
	v_and_b32_e32 v101, 0xffff0000, v169
	v_mfma_f32_16x16x32_bf16 v[34:37], v[82:85], v[74:77], v[34:37]
	ds_read_b128 v[82:85], v204 offset:40960
	v_mov_b32_e32 v166, v147
	v_mfma_f32_16x16x32_bf16 v[26:29], v[86:89], v[106:109], v[26:29]
	v_mfma_f32_16x16x32_bf16 v[34:37], v[86:89], v[102:105], v[34:37]
	ds_read_b128 v[86:89], v2 offset:43008
	s_waitcnt lgkmcnt(2)
	v_mfma_f32_16x16x32_bf16 v[38:41], v[78:81], v[70:73], v[38:41]
	v_mfma_f32_16x16x32_bf16 v[42:45], v[78:81], v[74:77], v[42:45]
	ds_read_b128 v[78:81], v2 offset:45056
	ds_read_b128 v[110:113], v2 offset:47104
	s_waitcnt lgkmcnt(3)
	v_mfma_f32_16x16x32_bf16 v[38:41], v[82:85], v[106:109], v[38:41]
	v_mfma_f32_16x16x32_bf16 v[42:45], v[82:85], v[102:105], v[42:45]
	ds_read_b128 v[82:85], v204 offset:45056
	ds_read_b128 v[114:117], v204 offset:47104
	s_waitcnt lgkmcnt(4)
	v_mfma_f32_16x16x32_bf16 v[62:65], v[86:89], v[70:73], v[62:65]
	v_mfma_f32_16x16x32_bf16 v[50:53], v[86:89], v[74:77], v[50:53]
	v_lshlrev_b32_e32 v86, 16, v164
	v_and_b32_e32 v87, 0xffff0000, v164
	v_lshlrev_b32_e32 v88, 16, v165
	s_waitcnt lgkmcnt(3)
	v_mfma_f32_16x16x32_bf16 v[58:61], v[78:81], v[70:73], v[58:61]
	v_and_b32_e32 v89, 0xffff0000, v165
	v_mfma_f32_16x16x32_bf16 v[54:57], v[78:81], v[74:77], v[54:57]
	v_lshlrev_b32_e32 v78, 16, v158
	v_and_b32_e32 v79, 0xffff0000, v158
	v_lshlrev_b32_e32 v80, 16, v159
	s_waitcnt lgkmcnt(2)
	v_mfma_f32_16x16x32_bf16 v[46:49], v[110:113], v[70:73], v[46:49]
	v_and_b32_e32 v81, 0xffff0000, v159
	v_lshlrev_b32_e32 v70, 16, v154
	v_and_b32_e32 v71, 0xffff0000, v154
	v_mfma_f32_16x16x32_bf16 v[66:69], v[110:113], v[74:77], v[66:69]
	v_lshlrev_b32_e32 v72, 16, v155
	v_and_b32_e32 v73, 0xffff0000, v155
	v_lshlrev_b32_e32 v74, 16, v152
	v_mfma_f32_16x16x32_bf16 v[62:65], v[90:93], v[106:109], v[62:65]
	v_and_b32_e32 v75, 0xffff0000, v152
	v_lshlrev_b32_e32 v76, 16, v153
	v_and_b32_e32 v77, 0xffff0000, v153
	v_mfma_f32_16x16x32_bf16 v[50:53], v[90:93], v[102:105], v[50:53]
	v_lshlrev_b32_e32 v90, 16, v160
	v_and_b32_e32 v91, 0xffff0000, v160
	v_lshlrev_b32_e32 v92, 16, v161
	s_waitcnt lgkmcnt(1)
	v_mfma_f32_16x16x32_bf16 v[58:61], v[82:85], v[106:109], v[58:61]
	v_and_b32_e32 v93, 0xffff0000, v161
	v_mfma_f32_16x16x32_bf16 v[54:57], v[82:85], v[102:105], v[54:57]
	v_lshlrev_b32_e32 v82, 16, v156
	v_and_b32_e32 v83, 0xffff0000, v156
	v_lshlrev_b32_e32 v84, 16, v157
	s_waitcnt lgkmcnt(0)
	v_mfma_f32_16x16x32_bf16 v[46:49], v[114:117], v[106:109], v[46:49]
	v_and_b32_e32 v85, 0xffff0000, v157
	v_mfma_f32_16x16x32_bf16 v[66:69], v[114:117], v[102:105], v[66:69]
